# ninth-round weight-conversion stream: nt hint on its once-read f32 weight loads and on the bf16 stores that are first read a layer later
# speedup vs baseline: 1.0138x; 1.0053x over previous
.LBB0_387:
	v_mov_b32_e32 v27, 0
	s_and_b64 vcc, exec, s[34:35]
	v_mov_b32_e32 v26, 0
	v_mov_b32_e32 v25, 0
	v_mov_b32_e32 v24, 0
	v_mov_b32_e32 v31, 0
	v_mov_b32_e32 v30, 0
	v_mov_b32_e32 v29, 0
	v_mov_b32_e32 v28, 0
	v_mov_b32_e32 v23, 0
	v_mov_b32_e32 v22, 0
	v_mov_b32_e32 v21, 0
	v_mov_b32_e32 v20, 0
	v_mov_b32_e32 v19, 0
	v_mov_b32_e32 v18, 0
	v_mov_b32_e32 v17, 0
	v_mov_b32_e32 v16, 0
	v_mov_b32_e32 v15, 0
	v_mov_b32_e32 v14, 0
	v_mov_b32_e32 v13, 0
	v_mov_b32_e32 v12, 0
	v_mov_b32_e32 v11, 0
	v_mov_b32_e32 v10, 0
	v_mov_b32_e32 v9, 0
	v_mov_b32_e32 v8, 0
	v_mov_b32_e32 v7, 0
	v_mov_b32_e32 v6, 0
	v_mov_b32_e32 v5, 0
	v_mov_b32_e32 v4, 0
	v_mov_b32_e32 v3, 0
	v_mov_b32_e32 v2, 0
	v_mov_b32_e32 v1, 0
	v_mov_b32_e32 v0, 0
	s_cbranch_vccz .LBB0_389
	v_lshlrev_b32_e32 v2, 1, v37
	v_lshlrev_b32_e32 v0, 2, v37
	v_lshlrev_b32_e32 v1, 4, v37
	v_and_b32_e32 v2, 12, v2
	v_and_b32_e32 v0, 28, v0
	v_and_or_b32 v1, v1, 16, v2
	v_cndmask_b32_e64 v0, v1, v0, s[10:11]
	v_add_u32_e32 v32, s7, v0
	v_lshrrev_b32_e32 v0, 3, v37
	v_add_u32_e32 v28, s41, v0
	v_mad_u64_u32 v[0:1], s[10:11], s12, v28, 0
	v_add_u32_e32 v2, 8, v28
	v_add_u32_e32 v8, 16, v28
	v_add_u32_e32 v10, 24, v28
	v_add_u32_e32 v16, 32, v28
	v_add_u32_e32 v18, 40, v28
	v_add_u32_e32 v26, 48, v28
	v_add_u32_e32 v28, 56, v28
	v_mad_u64_u32 v[2:3], s[10:11], s12, v2, 0
	v_mad_u64_u32 v[8:9], s[10:11], s12, v8, 0
	v_mad_u64_u32 v[10:11], s[10:11], s12, v10, 0
	v_mad_u64_u32 v[16:17], s[10:11], s12, v16, 0
	v_mad_u64_u32 v[18:19], s[10:11], s12, v18, 0
	v_mad_u64_u32 v[26:27], s[10:11], s12, v26, 0
	v_mad_u64_u32 v[28:29], s[10:11], s12, v28, 0
	v_lshl_add_u64 v[0:1], v[0:1], 2, s[8:9]
	v_lshlrev_b64 v[24:25], 2, v[32:33]
	v_lshl_add_u64 v[2:3], v[2:3], 2, s[8:9]
	v_lshl_add_u64 v[8:9], v[8:9], 2, s[8:9]
	v_lshl_add_u64 v[10:11], v[10:11], 2, s[8:9]
	v_lshl_add_u64 v[16:17], v[16:17], 2, s[8:9]
	v_lshl_add_u64 v[18:19], v[18:19], 2, s[8:9]
	v_lshl_add_u64 v[26:27], v[26:27], 2, s[8:9]
	v_lshl_add_u64 v[28:29], v[28:29], 2, s[8:9]
	v_lshl_add_u64 v[0:1], v[0:1], 0, v[24:25]
	v_lshl_add_u64 v[4:5], v[2:3], 0, v[24:25]
	v_lshl_add_u64 v[8:9], v[8:9], 0, v[24:25]
	v_lshl_add_u64 v[12:13], v[10:11], 0, v[24:25]
	v_lshl_add_u64 v[16:17], v[16:17], 0, v[24:25]
	v_lshl_add_u64 v[20:21], v[18:19], 0, v[24:25]
	v_lshl_add_u64 v[26:27], v[26:27], 0, v[24:25]
	v_lshl_add_u64 v[24:25], v[28:29], 0, v[24:25]
	global_load_dwordx4 v[0:3], v[0:1], off nt
	s_nop 0
	global_load_dwordx4 v[4:7], v[4:5], off nt
	s_nop 0
	global_load_dwordx4 v[8:11], v[8:9], off nt
	s_nop 0
	global_load_dwordx4 v[12:15], v[12:13], off nt
	s_nop 0
	global_load_dwordx4 v[16:19], v[16:17], off nt
	s_nop 0
	global_load_dwordx4 v[20:23], v[20:21], off nt
	s_nop 0
	global_load_dwordx4 v[28:31], v[26:27], off nt
	s_nop 0
	global_load_dwordx4 v[24:27], v[24:25], off nt

.LBB0_408:
	v_add_u32_e32 v32, s52, v32
	s_waitcnt vmcnt(0)
	v_lshlrev_b64 v[62:63], 2, v[32:33]
	v_add_u32_e32 v32, s0, v72
	v_mad_u64_u32 v[40:41], s[48:49], s46, v32, 0
	v_add_u32_e32 v32, s0, v73
	v_mad_u64_u32 v[46:47], s[48:49], s46, v32, 0
	v_add_u32_e32 v32, s0, v74
	v_mad_u64_u32 v[48:49], s[48:49], s46, v32, 0
	v_add_u32_e32 v32, s0, v75
	v_mad_u64_u32 v[54:55], s[48:49], s46, v32, 0
	v_add_u32_e32 v32, s0, v76
	v_mad_u64_u32 v[56:57], s[48:49], s46, v32, 0
	v_add_u32_e32 v32, s0, v77
	v_add_u32_e32 v38, s0, v71
	v_mad_u64_u32 v[64:65], s[48:49], s46, v32, 0
	v_add_u32_e32 v32, s0, v78
	v_mad_u64_u32 v[38:39], s[48:49], s46, v38, 0
	v_mad_u64_u32 v[66:67], s[46:47], s46, v32, 0
	v_lshl_add_u64 v[38:39], v[38:39], 2, s[34:35]
	v_lshl_add_u64 v[40:41], v[40:41], 2, s[34:35]
	v_lshl_add_u64 v[46:47], v[46:47], 2, s[34:35]
	v_lshl_add_u64 v[48:49], v[48:49], 2, s[34:35]
	v_lshl_add_u64 v[54:55], v[54:55], 2, s[34:35]
	v_lshl_add_u64 v[56:57], v[56:57], 2, s[34:35]
	v_lshl_add_u64 v[64:65], v[64:65], 2, s[34:35]
	v_lshl_add_u64 v[66:67], v[66:67], 2, s[34:35]
	v_lshl_add_u64 v[38:39], v[38:39], 0, v[62:63]
	v_lshl_add_u64 v[40:41], v[40:41], 0, v[62:63]
	v_lshl_add_u64 v[46:47], v[46:47], 0, v[62:63]
	v_lshl_add_u64 v[48:49], v[48:49], 0, v[62:63]
	v_lshl_add_u64 v[54:55], v[54:55], 0, v[62:63]
	v_lshl_add_u64 v[56:57], v[56:57], 0, v[62:63]
	v_lshl_add_u64 v[64:65], v[64:65], 0, v[62:63]
	v_lshl_add_u64 v[62:63], v[66:67], 0, v[62:63]
	global_load_dwordx4 v[42:45], v[38:39], off nt
	s_nop 0
	global_load_dwordx4 v[38:41], v[40:41], off nt
	s_nop 0
	global_load_dwordx4 v[50:53], v[46:47], off nt
	s_nop 0
	global_load_dwordx4 v[46:49], v[48:49], off nt
	s_nop 0
	global_load_dwordx4 v[58:61], v[54:55], off nt
	s_nop 0
	global_load_dwordx4 v[54:57], v[56:57], off nt
	s_nop 0
	global_load_dwordx4 v[66:69], v[64:65], off nt
	s_nop 0
	global_load_dwordx4 v[62:65], v[62:63], off nt

.LBB0_420:
	s_and_b64 vcc, exec, s[56:57]
	s_cbranch_vccz .LBB0_422
	v_add_u32_e32 v32, v79, v80
	v_add_u32_e32 v82, 0x420, v32
	s_waitcnt vmcnt(7)
	ds_write2_b32 v32, v0, v1 offset1:1
	ds_write2_b32 v32, v2, v3 offset0:2 offset1:3
	s_waitcnt vmcnt(6)
	ds_write2_b32 v82, v4, v5 offset1:1
	v_add_u32_e32 v82, 0x428, v32
	ds_write2_b32 v82, v6, v7 offset1:1
	v_add_u32_e32 v82, 0x840, v32
	s_waitcnt vmcnt(5)
	ds_write2_b32 v82, v8, v9 offset1:1
	v_add_u32_e32 v82, 0x848, v32
	ds_write2_b32 v82, v10, v11 offset1:1
	v_add_u32_e32 v82, 0xc60, v32
	s_waitcnt vmcnt(4)
	ds_write2_b32 v82, v12, v13 offset1:1
	v_add_u32_e32 v82, 0xc68, v32
	ds_write2_b32 v82, v14, v15 offset1:1
	v_add_u32_e32 v82, 0x1080, v32
	s_waitcnt vmcnt(3)
	ds_write2_b32 v82, v16, v17 offset1:1
	v_add_u32_e32 v82, 0x1088, v32
	ds_write2_b32 v82, v18, v19 offset1:1
	v_add_u32_e32 v82, 0x14a0, v32
	s_waitcnt vmcnt(2)
	ds_write2_b32 v82, v20, v21 offset1:1
	v_add_u32_e32 v82, 0x14a8, v32
	ds_write2_b32 v82, v22, v23 offset1:1
	v_add_u32_e32 v82, 0x18c0, v32
	s_waitcnt vmcnt(1)
	ds_write2_b32 v82, v28, v29 offset1:1
	v_add_u32_e32 v82, 0x18c8, v32
	ds_write2_b32 v82, v30, v31 offset1:1
	v_add_u32_e32 v82, 0x1ce0, v32
	v_add_u32_e32 v32, 0x1ce8, v32
	s_waitcnt vmcnt(0)
	ds_write2_b32 v82, v24, v25 offset1:1
	ds_write2_b32 v32, v26, v27 offset1:1
	s_waitcnt lgkmcnt(0)
	ds_read2_b32 v[86:87], v81 offset0:33 offset1:41
	ds_read2_b32 v[88:89], v81 offset1:8
	ds_read2_b32 v[90:91], v81 offset0:66 offset1:74
	ds_read2_b32 v[92:93], v81 offset0:99 offset1:107
	ds_read2_b32 v[94:95], v81 offset0:132 offset1:140
	ds_read2_b32 v[96:97], v81 offset0:165 offset1:173
	ds_read2_b32 v[98:99], v81 offset0:198 offset1:206
	ds_read2_b32 v[100:101], v81 offset0:231 offset1:239
	v_or_b32_e32 v32, s0, v71
	v_mul_hi_u32_u24_e32 v103, s34, v32
	v_mul_u32_u24_e32 v102, s34, v32
	v_lshl_add_u64 v[102:103], v[102:103], 1, s[46:47]
	s_lshl_b64 s[52:53], s[52:53], 1
	s_mov_b32 s49, s93
	v_lshl_add_u64 v[102:103], v[102:103], 0, s[52:53]
	s_lshl_b64 s[48:49], s[48:49], 1
	v_lshl_add_u64 v[102:103], v[102:103], 0, s[48:49]
	v_lshlrev_b32_e32 v32, 1, v34
	s_waitcnt lgkmcnt(6)
	v_cvt_pk_bf16_f32 v82, v88, v86
	s_waitcnt lgkmcnt(4)
	v_cvt_pk_bf16_f32 v83, v90, v92
	s_waitcnt lgkmcnt(2)
	v_cvt_pk_bf16_f32 v84, v94, v96
	s_waitcnt lgkmcnt(0)
	v_cvt_pk_bf16_f32 v85, v98, v100
	v_lshl_add_u64 v[102:103], v[102:103], 0, v[32:33]
	v_or_b32_e32 v86, s0, v72
	global_store_dwordx4 v[102:103], v[82:85], off nt
	s_nop 1
	v_cvt_pk_bf16_f32 v82, v89, v87
	v_mul_hi_u32_u24_e32 v87, s34, v86
	v_mul_u32_u24_e32 v86, s34, v86
	v_lshl_add_u64 v[86:87], v[86:87], 1, s[46:47]
	v_lshl_add_u64 v[86:87], v[86:87], 0, s[52:53]
	v_lshl_add_u64 v[86:87], v[86:87], 0, s[48:49]
	v_cvt_pk_bf16_f32 v83, v91, v93
	v_cvt_pk_bf16_f32 v84, v95, v97
	v_cvt_pk_bf16_f32 v85, v99, v101
	v_lshl_add_u64 v[86:87], v[86:87], 0, v[32:33]
	global_store_dwordx4 v[86:87], v[82:85], off nt
	ds_read2_b32 v[86:87], v81 offset0:16 offset1:24
	ds_read2_b32 v[88:89], v81 offset0:49 offset1:57
	ds_read2_b32 v[90:91], v81 offset0:82 offset1:90
	ds_read2_b32 v[92:93], v81 offset0:115 offset1:123
	ds_read2_b32 v[94:95], v81 offset0:148 offset1:156
	ds_read2_b32 v[96:97], v81 offset0:181 offset1:189
	ds_read2_b32 v[98:99], v81 offset0:214 offset1:222
	ds_read2_b32 v[100:101], v81 offset0:247 offset1:255
	s_waitcnt lgkmcnt(6)
	v_cvt_pk_bf16_f32 v82, v86, v88
	v_or_b32_e32 v86, s0, v73
	v_mul_hi_u32_u24_e32 v103, s34, v86
	v_mul_u32_u24_e32 v102, s34, v86
	v_lshl_add_u64 v[102:103], v[102:103], 1, s[46:47]
	v_lshl_add_u64 v[102:103], v[102:103], 0, s[52:53]
	v_lshl_add_u64 v[102:103], v[102:103], 0, s[48:49]
	s_waitcnt lgkmcnt(4)
	v_cvt_pk_bf16_f32 v83, v90, v92
	s_waitcnt lgkmcnt(2)
	v_cvt_pk_bf16_f32 v84, v94, v96
	s_waitcnt lgkmcnt(0)
	v_cvt_pk_bf16_f32 v85, v98, v100
	v_lshl_add_u64 v[102:103], v[102:103], 0, v[32:33]
	v_or_b32_e32 v86, s0, v74
	global_store_dwordx4 v[102:103], v[82:85], off nt
	s_nop 1
	v_cvt_pk_bf16_f32 v82, v87, v89
	v_mul_hi_u32_u24_e32 v87, s34, v86
	v_mul_u32_u24_e32 v86, s34, v86
	v_lshl_add_u64 v[86:87], v[86:87], 1, s[46:47]
	v_lshl_add_u64 v[86:87], v[86:87], 0, s[52:53]
	v_lshl_add_u64 v[86:87], v[86:87], 0, s[48:49]
	v_cvt_pk_bf16_f32 v83, v91, v93
	v_cvt_pk_bf16_f32 v84, v95, v97
	v_cvt_pk_bf16_f32 v85, v99, v101
	v_lshl_add_u64 v[86:87], v[86:87], 0, v[32:33]
	global_store_dwordx4 v[86:87], v[82:85], off nt
	s_waitcnt lgkmcnt(0)

.LBB0_439:
	s_waitcnt vmcnt(7)
	v_add_u32_e32 v0, s0, v71
	v_add_u32_e32 v2, s0, v72
	s_waitcnt vmcnt(5)
	v_add_u32_e32 v8, s0, v73
	v_add_u32_e32 v10, s0, v74
	s_waitcnt vmcnt(3)
	v_add_u32_e32 v16, s0, v75
	v_add_u32_e32 v18, s0, v76
	s_waitcnt vmcnt(0)
	v_add_u32_e32 v26, s0, v77
	v_add_u32_e32 v28, s0, v78
	v_add_u32_e32 v32, s52, v32
	v_mad_u64_u32 v[0:1], s[48:49], s46, v0, 0
	v_mad_u64_u32 v[2:3], s[48:49], s46, v2, 0
	v_mad_u64_u32 v[8:9], s[48:49], s46, v8, 0
	v_mad_u64_u32 v[10:11], s[48:49], s46, v10, 0
	v_mad_u64_u32 v[16:17], s[48:49], s46, v16, 0
	v_mad_u64_u32 v[18:19], s[48:49], s46, v18, 0
	v_mad_u64_u32 v[26:27], s[48:49], s46, v26, 0
	v_mad_u64_u32 v[28:29], s[46:47], s46, v28, 0
	v_lshl_add_u64 v[0:1], v[0:1], 2, s[34:35]
	v_lshlrev_b64 v[24:25], 2, v[32:33]
	v_lshl_add_u64 v[2:3], v[2:3], 2, s[34:35]
	v_lshl_add_u64 v[8:9], v[8:9], 2, s[34:35]
	v_lshl_add_u64 v[10:11], v[10:11], 2, s[34:35]
	v_lshl_add_u64 v[16:17], v[16:17], 2, s[34:35]
	v_lshl_add_u64 v[18:19], v[18:19], 2, s[34:35]
	v_lshl_add_u64 v[26:27], v[26:27], 2, s[34:35]
	v_lshl_add_u64 v[28:29], v[28:29], 2, s[34:35]
	v_lshl_add_u64 v[0:1], v[0:1], 0, v[24:25]
	v_lshl_add_u64 v[4:5], v[2:3], 0, v[24:25]
	v_lshl_add_u64 v[8:9], v[8:9], 0, v[24:25]
	v_lshl_add_u64 v[12:13], v[10:11], 0, v[24:25]
	v_lshl_add_u64 v[16:17], v[16:17], 0, v[24:25]
	v_lshl_add_u64 v[20:21], v[18:19], 0, v[24:25]
	v_lshl_add_u64 v[26:27], v[26:27], 0, v[24:25]
	v_lshl_add_u64 v[24:25], v[28:29], 0, v[24:25]
	global_load_dwordx4 v[0:3], v[0:1], off nt
	s_nop 0
	global_load_dwordx4 v[4:7], v[4:5], off nt
	s_nop 0
	global_load_dwordx4 v[8:11], v[8:9], off nt
	s_nop 0
	global_load_dwordx4 v[12:15], v[12:13], off nt
	s_nop 0
	global_load_dwordx4 v[16:19], v[16:17], off nt
	s_nop 0
	global_load_dwordx4 v[20:23], v[20:21], off nt
	s_nop 0
	global_load_dwordx4 v[28:31], v[26:27], off nt
	s_nop 0
	global_load_dwordx4 v[24:27], v[24:25], off nt

.LBB0_452:
	s_and_b64 vcc, exec, s[52:53]
	s_cbranch_vccz .LBB0_390
	v_add_u32_e32 v32, v79, v80
	v_add_u32_e32 v82, 0x420, v32
	s_waitcnt vmcnt(7)
	ds_write2_b32 v32, v42, v43 offset1:1
	ds_write2_b32 v32, v44, v45 offset0:2 offset1:3
	s_waitcnt vmcnt(6)
	ds_write2_b32 v82, v38, v39 offset1:1
	v_add_u32_e32 v82, 0x428, v32
	ds_write2_b32 v82, v40, v41 offset1:1
	v_add_u32_e32 v82, 0x840, v32
	s_waitcnt vmcnt(5)
	ds_write2_b32 v82, v50, v51 offset1:1
	v_add_u32_e32 v82, 0x848, v32
	ds_write2_b32 v82, v52, v53 offset1:1
	v_add_u32_e32 v82, 0xc60, v32
	s_waitcnt vmcnt(4)
	ds_write2_b32 v82, v46, v47 offset1:1
	v_add_u32_e32 v82, 0xc68, v32
	ds_write2_b32 v82, v48, v49 offset1:1
	v_add_u32_e32 v82, 0x1080, v32
	s_waitcnt vmcnt(3)
	ds_write2_b32 v82, v58, v59 offset1:1
	v_add_u32_e32 v82, 0x1088, v32
	ds_write2_b32 v82, v60, v61 offset1:1
	v_add_u32_e32 v82, 0x14a0, v32
	s_waitcnt vmcnt(2)
	ds_write2_b32 v82, v54, v55 offset1:1
	v_add_u32_e32 v82, 0x14a8, v32
	ds_write2_b32 v82, v56, v57 offset1:1
	v_add_u32_e32 v82, 0x18c0, v32
	s_waitcnt vmcnt(1)
	ds_write2_b32 v82, v66, v67 offset1:1
	v_add_u32_e32 v82, 0x18c8, v32
	ds_write2_b32 v82, v68, v69 offset1:1
	v_add_u32_e32 v82, 0x1ce0, v32
	v_add_u32_e32 v32, 0x1ce8, v32
	s_waitcnt vmcnt(0)
	ds_write2_b32 v82, v62, v63 offset1:1
	ds_write2_b32 v32, v64, v65 offset1:1
	s_waitcnt lgkmcnt(0)
	ds_read2_b32 v[86:87], v81 offset0:33 offset1:41
	ds_read2_b32 v[88:89], v81 offset1:8
	ds_read2_b32 v[90:91], v81 offset0:66 offset1:74
	ds_read2_b32 v[92:93], v81 offset0:99 offset1:107
	ds_read2_b32 v[94:95], v81 offset0:132 offset1:140
	ds_read2_b32 v[96:97], v81 offset0:165 offset1:173
	ds_read2_b32 v[98:99], v81 offset0:198 offset1:206
	ds_read2_b32 v[100:101], v81 offset0:231 offset1:239
	v_or_b32_e32 v32, s0, v71
	v_mul_hi_u32_u24_e32 v103, s34, v32
	v_mul_u32_u24_e32 v102, s34, v32
	v_lshl_add_u64 v[102:103], v[102:103], 1, s[42:43]
	s_lshl_b64 s[48:49], s[48:49], 1
	s_mov_b32 s47, s93
	v_lshl_add_u64 v[102:103], v[102:103], 0, s[48:49]
	s_lshl_b64 s[46:47], s[46:47], 1
	v_lshl_add_u64 v[102:103], v[102:103], 0, s[46:47]
	v_lshlrev_b32_e32 v32, 1, v34
	s_waitcnt lgkmcnt(6)
	v_cvt_pk_bf16_f32 v82, v88, v86
	s_waitcnt lgkmcnt(4)
	v_cvt_pk_bf16_f32 v83, v90, v92
	s_waitcnt lgkmcnt(2)
	v_cvt_pk_bf16_f32 v84, v94, v96
	s_waitcnt lgkmcnt(0)
	v_cvt_pk_bf16_f32 v85, v98, v100
	v_lshl_add_u64 v[102:103], v[102:103], 0, v[32:33]
	v_or_b32_e32 v86, s0, v72
	global_store_dwordx4 v[102:103], v[82:85], off nt
	s_nop 1
	v_cvt_pk_bf16_f32 v82, v89, v87
	v_mul_hi_u32_u24_e32 v87, s34, v86
	v_mul_u32_u24_e32 v86, s34, v86
	v_lshl_add_u64 v[86:87], v[86:87], 1, s[42:43]
	v_lshl_add_u64 v[86:87], v[86:87], 0, s[48:49]
	v_lshl_add_u64 v[86:87], v[86:87], 0, s[46:47]
	v_cvt_pk_bf16_f32 v83, v91, v93
	v_cvt_pk_bf16_f32 v84, v95, v97
	v_cvt_pk_bf16_f32 v85, v99, v101
	v_lshl_add_u64 v[86:87], v[86:87], 0, v[32:33]
	global_store_dwordx4 v[86:87], v[82:85], off nt
	ds_read2_b32 v[86:87], v81 offset0:16 offset1:24
	ds_read2_b32 v[88:89], v81 offset0:49 offset1:57
	ds_read2_b32 v[90:91], v81 offset0:82 offset1:90
	ds_read2_b32 v[92:93], v81 offset0:115 offset1:123
	ds_read2_b32 v[94:95], v81 offset0:148 offset1:156
	ds_read2_b32 v[96:97], v81 offset0:181 offset1:189
	ds_read2_b32 v[98:99], v81 offset0:214 offset1:222
	ds_read2_b32 v[100:101], v81 offset0:247 offset1:255
	s_waitcnt lgkmcnt(6)
	v_cvt_pk_bf16_f32 v82, v86, v88
	v_or_b32_e32 v86, s0, v73
	v_mul_hi_u32_u24_e32 v103, s34, v86
	v_mul_u32_u24_e32 v102, s34, v86
	v_lshl_add_u64 v[102:103], v[102:103], 1, s[42:43]
	v_lshl_add_u64 v[102:103], v[102:103], 0, s[48:49]
	v_lshl_add_u64 v[102:103], v[102:103], 0, s[46:47]
	s_waitcnt lgkmcnt(4)
	v_cvt_pk_bf16_f32 v83, v90, v92
	s_waitcnt lgkmcnt(2)
	v_cvt_pk_bf16_f32 v84, v94, v96
	s_waitcnt lgkmcnt(0)
	v_cvt_pk_bf16_f32 v85, v98, v100
	v_lshl_add_u64 v[102:103], v[102:103], 0, v[32:33]
	v_or_b32_e32 v86, s0, v74
	global_store_dwordx4 v[102:103], v[82:85], off nt
	s_nop 1
	v_cvt_pk_bf16_f32 v82, v87, v89
	v_mul_hi_u32_u24_e32 v87, s34, v86
	v_mul_u32_u24_e32 v86, s34, v86
	v_lshl_add_u64 v[86:87], v[86:87], 1, s[42:43]
	v_lshl_add_u64 v[86:87], v[86:87], 0, s[48:49]
	v_lshl_add_u64 v[86:87], v[86:87], 0, s[46:47]
	v_cvt_pk_bf16_f32 v83, v91, v93
	v_cvt_pk_bf16_f32 v84, v95, v97
	v_cvt_pk_bf16_f32 v85, v99, v101
	v_lshl_add_u64 v[86:87], v[86:87], 0, v[32:33]
	global_store_dwordx4 v[86:87], v[82:85], off nt
	s_waitcnt lgkmcnt(0)
	s_branch .LBB0_390
